# GUP meta-row skinny GEMM tail: conv-weight + rstd loads hoisted to the item top, LDS reduction reads batched; stacked on the prologue DMA de-serialization
# speedup vs baseline: 1.0078x; 1.0042x over previous
.LBB0_277:
	s_and_b32 s18, s15, 0xffffff00
	s_and_b32 s19, s2, 0x70
	s_or_b32 s18, s19, s18
	v_or_b32_e32 v2, s18, v177
	v_ashrrev_i32_e32 v3, 31, v2
	v_lshlrev_b64 v[4:5], 11, v[2:3]
	v_lshl_add_u64 v[32:33], v[20:21], 0, v[4:5]
	v_or_b32_e32 v6, 0x80, v2
	v_ashrrev_i32_e32 v7, 31, v6
	v_lshlrev_b64 v[6:7], 11, v[6:7]
	v_lshl_add_u64 v[42:43], v[20:21], 0, v[6:7]
	global_load_dwordx4 v[44:47], v[32:33], off
	global_load_dwordx4 v[48:51], v[18:19], off
	global_load_dwordx4 v[52:55], v[42:43], off
	global_load_dwordx4 v[56:59], v[32:33], off offset:64
	global_load_dwordx4 v[60:63], v[18:19], off offset:64
	global_load_dwordx4 v[64:67], v[42:43], off offset:64
	global_load_dwordx4 v[68:71], v[32:33], off offset:128
	global_load_dwordx4 v[88:91], v[18:19], off offset:128
	global_load_dwordx4 v[92:95], v[42:43], off offset:128
	global_load_dwordx4 v[96:99], v[32:33], off offset:192
	global_load_dwordx4 v[100:103], v[18:19], off offset:192
	global_load_dwordx4 v[104:107], v[42:43], off offset:192
	v_add_u32_e32 v28, s2, v34
	v_ashrrev_i32_e32 v29, 31, v28
	v_lshlrev_b64 v[14:15], 2, v[28:29]
	v_lshl_add_u64 v[6:7], s[44:45], 0, v[14:15]
	v_lshl_add_u64 v[10:11], s[50:51], 0, v[14:15]
	v_lshl_add_u64 v[14:15], s[62:63], 0, v[14:15]
	global_load_dwordx4 v[124:127], v[6:7], off
	global_load_dwordx4 v[128:131], v[10:11], off
	global_load_dwordx4 v[132:135], v[14:15], off
	global_load_dword v136, v[22:23], off
	s_andn2_b64 vcc, exec, s[26:27]
	s_waitcnt vmcnt(14)
	v_mfma_f32_16x16x32_bf16 v[2:5], v[44:47], v[48:51], 0
	s_waitcnt vmcnt(13)
	v_mfma_f32_16x16x32_bf16 v[6:9], v[52:55], v[48:51], 0
	s_waitcnt vmcnt(11)
	v_mfma_f32_16x16x32_bf16 v[2:5], v[56:59], v[60:63], v[2:5]
	s_waitcnt vmcnt(10)
	v_mfma_f32_16x16x32_bf16 v[6:9], v[64:67], v[60:63], v[6:9]
	s_waitcnt vmcnt(8)
	v_mfma_f32_16x16x32_bf16 v[2:5], v[68:71], v[88:91], v[2:5]
	s_waitcnt vmcnt(7)
	v_mfma_f32_16x16x32_bf16 v[6:9], v[92:95], v[88:91], v[6:9]
	s_waitcnt vmcnt(5)
	v_mfma_f32_16x16x32_bf16 v[2:5], v[96:99], v[100:103], v[2:5]
	s_waitcnt vmcnt(4)
	v_mfma_f32_16x16x32_bf16 v[6:9], v[104:107], v[100:103], v[6:9]
	s_nop 6
	ds_write_b128 v0, v[2:5]
	ds_write_b128 v0, v[6:9] offset:16
	s_waitcnt lgkmcnt(0)
	s_barrier
	s_cbranch_vccnz .LBB0_276
	v_and_b32_e32 v38, 64, v231
	ds_read_b128 v[44:47], v37 offset:2048
	ds_read_b128 v[48:51], v37 offset:2064
	ds_read_b128 v[52:55], v37 offset:4096
	ds_read_b128 v[56:59], v37 offset:4112
	ds_read_b128 v[60:63], v37 offset:6144
	ds_read_b128 v[64:67], v37 offset:6160
	ds_read_b128 v[68:71], v37 offset:8192
	ds_read_b128 v[88:91], v37 offset:8208
	ds_read_b128 v[92:95], v37 offset:10240
	ds_read_b128 v[96:99], v37 offset:10256
	ds_read_b128 v[100:103], v37 offset:12288
	ds_read_b128 v[104:107], v37 offset:12304
	ds_read_b128 v[108:111], v37 offset:14336
	ds_read_b128 v[112:115], v37 offset:14352
	v_or_b32_e32 v39, v38, v35
	v_or_b32_e32 v38, v38, v36
	v_lshlrev_b32_e32 v42, 2, v39
	v_lshlrev_b32_e32 v43, 2, v38
	s_waitcnt lgkmcnt(13)
	v_pk_add_f32 v[12:13], v[4:5], v[46:47]
	v_pk_add_f32 v[10:11], v[2:3], v[44:45]
	s_waitcnt lgkmcnt(12)
	v_pk_add_f32 v[8:9], v[8:9], v[50:51]
	v_pk_add_f32 v[6:7], v[6:7], v[48:49]
	s_waitcnt lgkmcnt(11)
	v_pk_add_f32 v[12:13], v[12:13], v[54:55]
	v_pk_add_f32 v[10:11], v[10:11], v[52:53]
	s_waitcnt lgkmcnt(10)
	v_pk_add_f32 v[8:9], v[8:9], v[58:59]
	v_pk_add_f32 v[6:7], v[6:7], v[56:57]
	s_waitcnt lgkmcnt(9)
	v_pk_add_f32 v[12:13], v[12:13], v[62:63]
	v_pk_add_f32 v[10:11], v[10:11], v[60:61]
	s_waitcnt lgkmcnt(8)
	v_pk_add_f32 v[8:9], v[8:9], v[66:67]
	v_pk_add_f32 v[6:7], v[6:7], v[64:65]
	s_waitcnt lgkmcnt(7)
	v_pk_add_f32 v[12:13], v[12:13], v[70:71]
	v_pk_add_f32 v[10:11], v[10:11], v[68:69]
	s_waitcnt lgkmcnt(6)
	v_pk_add_f32 v[8:9], v[8:9], v[90:91]
	v_pk_add_f32 v[6:7], v[6:7], v[88:89]
	s_waitcnt lgkmcnt(5)
	v_pk_add_f32 v[12:13], v[12:13], v[94:95]
	v_pk_add_f32 v[10:11], v[10:11], v[92:93]
	s_waitcnt lgkmcnt(4)
	v_pk_add_f32 v[8:9], v[8:9], v[98:99]
	v_pk_add_f32 v[6:7], v[6:7], v[96:97]
	s_waitcnt lgkmcnt(3)
	v_pk_add_f32 v[12:13], v[12:13], v[102:103]
	v_pk_add_f32 v[10:11], v[10:11], v[100:101]
	s_waitcnt lgkmcnt(2)
	v_pk_add_f32 v[8:9], v[8:9], v[106:107]
	v_pk_add_f32 v[6:7], v[6:7], v[104:105]
	s_waitcnt lgkmcnt(1)
	v_pk_add_f32 v[12:13], v[12:13], v[110:111]
	v_pk_add_f32 v[10:11], v[10:11], v[108:109]
	s_waitcnt lgkmcnt(0)
	v_pk_add_f32 v[8:9], v[8:9], v[114:115]
	v_pk_add_f32 v[6:7], v[6:7], v[112:113]
	s_waitcnt vmcnt(0)
	v_pk_mul_f32 v[4:5], v[12:13], v[136:137] op_sel_hi:[1,0]
	v_pk_mul_f32 v[2:3], v[10:11], v[136:137] op_sel_hi:[1,0]
	v_pk_mul_f32 v[30:31], v[8:9], v[136:137] op_sel_hi:[1,0]
	v_pk_mul_f32 v[32:33], v[6:7], v[136:137] op_sel_hi:[1,0]
	v_mov_b64_e32 v[6:7], v[124:125]
	v_mov_b64_e32 v[8:9], v[126:127]
	v_mov_b64_e32 v[10:11], v[128:129]
	v_mov_b64_e32 v[12:13], v[130:131]
	v_mov_b64_e32 v[14:15], v[132:133]
	v_mov_b64_e32 v[16:17], v[134:135]
	ds_bpermute_b32 v38, v42, v2
	ds_bpermute_b32 v40, v43, v2
	s_waitcnt lgkmcnt(1)
	v_cndmask_b32_e64 v39, v38, 0, s[38:39]
	v_mov_b32_e32 v38, v2
	s_waitcnt lgkmcnt(0)
	v_cndmask_b32_e64 v44, 0, v40, s[40:41]
	s_waitcnt vmcnt(1)
	v_mov_b32_e32 v41, v10
	s_waitcnt vmcnt(0)
	v_mov_b32_e32 v40, v14
	v_pk_mul_f32 v[38:39], v[40:41], v[38:39]
	s_nop 0
	v_fma_f32 v6, v6, v44, v39
	v_add_f32_e32 v6, v38, v6
	v_mul_f32_e32 v10, 0xbfb8aa3b, v6
	v_exp_f32_e32 v10, v10
	v_mov_b32_e32 v38, v3
	v_add_f32_e32 v10, 1.0, v10
	v_rcp_f32_e32 v10, v10
	s_nop 0
	v_mul_f32_e32 v6, v6, v10
	v_mul_f32_e32 v14, v32, v6
	ds_bpermute_b32 v6, v42, v3
	ds_bpermute_b32 v10, v43, v3
	s_waitcnt lgkmcnt(1)
	v_cndmask_b32_e64 v39, v6, 0, s[38:39]
	s_waitcnt lgkmcnt(0)
	v_cndmask_b32_e64 v6, 0, v10, s[40:41]
	v_mov_b32_e32 v10, v15
	v_pk_mul_f32 v[10:11], v[10:11], v[38:39]
	s_nop 0
	v_fma_f32 v6, v7, v6, v11
	v_add_f32_e32 v6, v10, v6
	v_mul_f32_e32 v7, 0xbfb8aa3b, v6
	v_exp_f32_e32 v7, v7
	ds_bpermute_b32 v10, v43, v4
	v_mov_b32_e32 v11, v12
	v_mov_b32_e32 v12, v17
	v_add_f32_e32 v7, 1.0, v7
	v_rcp_f32_e32 v7, v7
	s_waitcnt lgkmcnt(0)
	v_cndmask_b32_e64 v32, 0, v10, s[40:41]
	v_mov_b32_e32 v10, v16
	v_mul_f32_e32 v6, v6, v7
	v_mul_f32_e32 v15, v33, v6
	ds_bpermute_b32 v6, v42, v4
	s_waitcnt lgkmcnt(0)
	v_cndmask_b32_e64 v7, v6, 0, s[38:39]
	v_mov_b32_e32 v6, v4
	v_pk_mul_f32 v[6:7], v[10:11], v[6:7]
	ds_bpermute_b32 v10, v43, v5
	v_fma_f32 v7, v8, v32, v7
	v_add_f32_e32 v6, v6, v7
	v_mul_f32_e32 v7, 0xbfb8aa3b, v6
	v_exp_f32_e32 v7, v7
	s_waitcnt lgkmcnt(0)
	v_cndmask_b32_e64 v10, 0, v10, s[40:41]
	v_add_f32_e32 v7, 1.0, v7
	v_rcp_f32_e32 v7, v7
	s_nop 0
	v_mul_f32_e32 v6, v6, v7
	v_mul_f32_e32 v8, v30, v6
	ds_bpermute_b32 v6, v42, v5
	s_waitcnt lgkmcnt(0)
	v_cndmask_b32_e64 v7, v6, 0, s[38:39]
	v_mov_b32_e32 v6, v5
	v_pk_mul_f32 v[6:7], v[12:13], v[6:7]
	s_nop 0
	v_fma_f32 v7, v9, v10, v7
	v_add_f32_e32 v6, v6, v7
	v_mul_f32_e32 v7, 0xbfb8aa3b, v6
	v_exp_f32_e32 v7, v7
	s_nop 0
	v_add_f32_e32 v7, 1.0, v7
	v_rcp_f32_e32 v7, v7
	s_nop 0
	v_mul_f32_e32 v6, v6, v7
	v_mul_f32_e32 v7, v31, v6
	v_cvt_pk_bf16_f32 v7, v8, v7
	v_lshl_add_u64 v[8:9], v[28:29], 1, v[24:25]
	v_cvt_pk_bf16_f32 v6, v14, v15
	global_store_dwordx2 v[8:9], v[6:7], off
	s_and_saveexec_b64 s[46:47], s[42:43]
	s_cbranch_execz .LBB0_275
	v_lshl_add_u64 v[6:7], v[28:29], 2, v[26:27]
	global_store_dwordx4 v[6:7], v[2:5], off
	s_branch .LBB0_275
.LBB0_280:
	s_nop 0
	s_nop 0
	s_nop 0
	s_nop 0
	s_nop 0
	s_nop 0
	s_nop 0
	s_nop 0
	s_nop 0
	s_nop 0
	s_nop 0
	s_nop 0
	s_nop 0
	s_nop 0
	s_nop 0
	s_nop 0
	s_nop 0
	s_nop 0
	s_nop 0
	s_nop 0
	s_nop 0
	s_nop 0
	s_nop 0
	s_nop 0
	s_nop 0
	s_mov_b64 s[26:27], 0
